# decode-step set-up loads issued together (one vmcnt wait per section) + scan_dn MFMA ring + solve loop prefetch + copies
# speedup vs baseline: 1.0212x; 1.0136x over previous
.LBB0_559:
	v_mov_b32_e32 v11, v176
	s_lshl_b32 s4, s44, 1
	s_addk_i32 s4, 0xfe00
	v_ashrrev_i32_e32 v9, 8, v11
	v_add_u32_e32 v26, s4, v9
	v_lshlrev_b32_e32 v0, 1, v26
	v_and_b32_e32 v15, -8, v0
	v_and_b32_e32 v13, 3, v26
	v_add_u32_e32 v4, 0x2000, v15
	v_mov_b64_e32 v[28:29], s[30:31]
	v_and_b32_e32 v189, 0xff, v11
	v_mad_i64_i32 v[0:1], s[4:5], v4, s37, v[28:29]
	v_lshlrev_b32_e32 v16, 9, v13
	v_lshl_add_u64 v[2:3], v[0:1], 0, v[16:17]
	v_lshlrev_b32_e32 v6, 1, v189
	v_mov_b32_e32 v7, v17
	v_lshl_add_u64 v[2:3], v[2:3], 0, v[6:7]
	v_add_co_u32_e32 v2, vcc, s39, v2
	v_add_u32_e32 v14, 0x2001, v15
	v_addc_co_u32_e32 v3, vcc, 0, v3, vcc
	global_load_ushort v240, v[2:3], off
	v_mad_i32_i24 v188, v9, s17, 0
	v_lshl_add_u32 v19, v189, 2, v188
	v_add_u32_e32 v24, 0x2005, v15
	v_mad_i64_i32 v[40:41], s[4:5], v24, s37, v[28:29]
	v_ashrrev_i32_e32 v5, 31, v4
	v_mad_i64_i32 v[2:3], s[4:5], v14, s37, v[28:29]
	v_lshl_add_u64 v[20:21], v[2:3], 0, v[16:17]
	v_lshl_add_u64 v[20:21], v[20:21], 0, v[6:7]
	v_add_co_u32_e32 v20, vcc, s39, v20
	s_nop 1
	v_addc_co_u32_e32 v21, vcc, 0, v21, vcc
	global_load_ushort v241, v[20:21], off
	v_add_u32_e32 v10, 0x2002, v15
	v_mad_i64_i32 v[34:35], s[4:5], v10, s37, v[28:29]
	v_lshl_add_u64 v[20:21], v[34:35], 0, v[16:17]
	v_lshl_add_u64 v[20:21], v[20:21], 0, v[6:7]
	v_add_co_u32_e32 v20, vcc, s39, v20
	s_nop 1
	v_addc_co_u32_e32 v21, vcc, 0, v21, vcc
	global_load_ushort v243, v[20:21], off
	v_add_u32_e32 v8, 0x2003, v15
	v_mad_i64_i32 v[36:37], s[4:5], v8, s37, v[28:29]
	v_lshl_add_u64 v[20:21], v[36:37], 0, v[16:17]
	v_lshl_add_u64 v[20:21], v[20:21], 0, v[6:7]
	v_add_co_u32_e32 v20, vcc, s39, v20
	s_nop 1
	v_addc_co_u32_e32 v21, vcc, 0, v21, vcc
	global_load_ushort v245, v[20:21], off
	v_add_u32_e32 v12, 0x2004, v15
	v_mad_i64_i32 v[38:39], s[4:5], v12, s37, v[28:29]
	v_lshl_add_u64 v[20:21], v[38:39], 0, v[16:17]
	v_lshl_add_u64 v[20:21], v[20:21], 0, v[6:7]
	v_add_co_u32_e32 v20, vcc, s39, v20
	s_nop 1
	v_addc_co_u32_e32 v21, vcc, 0, v21, vcc
	global_load_ushort v248, v[20:21], off
	v_lshl_add_u64 v[20:21], v[40:41], 0, v[16:17]
	v_lshl_add_u64 v[20:21], v[20:21], 0, v[6:7]
	v_add_co_u32_e32 v20, vcc, s39, v20
	s_nop 1
	v_addc_co_u32_e32 v21, vcc, 0, v21, vcc
	global_load_ushort v249, v[20:21], off
	v_add_u32_e32 v22, 0x2006, v15
	v_mad_i64_i32 v[42:43], s[4:5], v22, s37, v[28:29]
	v_lshl_add_u64 v[20:21], v[42:43], 0, v[16:17]
	v_lshl_add_u64 v[20:21], v[20:21], 0, v[6:7]
	v_add_co_u32_e32 v20, vcc, s39, v20
	s_nop 1
	v_addc_co_u32_e32 v21, vcc, 0, v21, vcc
	global_load_ushort v252, v[20:21], off
	v_add_u32_e32 v20, 0x2007, v15
	v_mad_i64_i32 v[44:45], s[4:5], v20, s37, v[28:29]
	v_lshl_add_u64 v[28:29], v[44:45], 0, v[16:17]
	v_lshl_add_u64 v[28:29], v[28:29], 0, v[6:7]
	v_add_co_u32_e32 v28, vcc, 0x3000, v28
	s_nop 1
	v_addc_co_u32_e32 v29, vcc, 0, v29, vcc
	global_load_ushort v253, v[28:29], off
	v_cmp_gt_u32_e32 vcc, 8, v189
	v_lshlrev_b32_e32 v28, 2, v13
	s_waitcnt vmcnt(0)
	v_lshlrev_b32_e32 v244, 16, v240
	v_lshlrev_b32_e32 v242, 16, v241
	ds_write2st64_b32 v19, v244, v242 offset0:96 offset1:100
	v_lshlrev_b32_e32 v246, 16, v243
	v_lshlrev_b32_e32 v247, 16, v245
	ds_write2st64_b32 v19, v246, v247 offset0:104 offset1:108
	v_lshlrev_b32_e32 v250, 16, v248
	v_lshlrev_b32_e32 v251, 16, v249
	ds_write2st64_b32 v19, v250, v251 offset0:112 offset1:116
	v_lshlrev_b32_e32 v21, 16, v252
	v_lshlrev_b32_e32 v7, 16, v253
	ds_write2st64_b32 v19, v21, v7 offset0:120 offset1:124
	s_and_saveexec_b64 s[4:5], vcc
	s_cbranch_execz .LBB0_561
	v_or_b32_e32 v30, v4, v189
	v_ashrrev_i32_e32 v31, 31, v30
	v_lshlrev_b64 v[30:31], 7, v[30:31]
	v_lshl_add_u64 v[30:31], s[80:81], 0, v[30:31]
	v_mov_b32_e32 v29, v17
	v_lshl_add_u64 v[32:33], v[30:31], 0, v[28:29]
	global_load_dword v7, v[32:33], off offset:80
	global_load_dword v15, v28, s[94:95]
	s_mov_b32 s6, 0xbfb8aa3b
	s_waitcnt vmcnt(0)
	v_add_f32_e32 v7, v7, v15
	v_min_f32_e32 v15, 0, v7
	v_mul_f32_e64 v7, |v7|, s6
	v_exp_f32_e32 v7, v7
	s_mov_b32 s6, 0x3f2aaaab
	v_add_f32_e32 v16, 1.0, v7
	v_add_f32_e32 v21, -1.0, v16
	v_sub_f32_e32 v23, v21, v16
	v_add_f32_e32 v23, 1.0, v23
	v_sub_f32_e32 v21, v7, v21
	v_add_f32_e32 v21, v21, v23
	v_frexp_mant_f32_e32 v23, v16
	v_cvt_f64_f32_e32 v[30:31], v16
	v_cmp_gt_f32_e32 vcc, s6, v23
	v_frexp_exp_i32_f64_e32 v23, v[30:31]
	s_mov_b32 s6, 0x3f317218
	v_subbrev_co_u32_e32 v23, vcc, 0, v23, vcc
	v_sub_u32_e32 v25, 0, v23
	v_ldexp_f32 v16, v16, v25
	v_ldexp_f32 v21, v21, v25
	v_add_f32_e32 v25, -1.0, v16
	v_add_f32_e32 v27, 1.0, v25
	v_sub_f32_e32 v27, v16, v27
	v_add_f32_e32 v27, v21, v27
	v_add_f32_e32 v29, v25, v27
	v_sub_f32_e32 v25, v29, v25
	v_sub_f32_e32 v25, v27, v25
	v_add_f32_e32 v27, 1.0, v16
	v_add_f32_e32 v30, -1.0, v27
	v_sub_f32_e32 v16, v16, v30
	v_add_f32_e32 v16, v21, v16
	v_add_f32_e32 v21, v27, v16
	v_sub_f32_e32 v27, v21, v27
	v_sub_f32_e32 v16, v16, v27
	v_rcp_f32_e32 v27, v21
	v_cvt_f32_i32_e32 v23, v23
	v_mul_f32_e32 v30, v29, v27
	v_mul_f32_e32 v31, v21, v30
	v_fma_f32 v46, v30, v21, -v31
	v_fmac_f32_e32 v46, v30, v16
	v_add_f32_e32 v47, v31, v46
	v_sub_f32_e32 v48, v29, v47
	v_sub_f32_e32 v29, v29, v48
	v_sub_f32_e32 v31, v47, v31
	v_sub_f32_e32 v29, v29, v47
	v_add_f32_e32 v25, v25, v29
	v_sub_f32_e32 v29, v31, v46
	v_add_f32_e32 v25, v29, v25
	v_add_f32_e32 v29, v48, v25
	v_mul_f32_e32 v31, v27, v29
	v_mul_f32_e32 v46, v21, v31
	v_fma_f32 v21, v31, v21, -v46
	v_fmac_f32_e32 v21, v31, v16
	v_sub_f32_e32 v16, v48, v29
	v_add_f32_e32 v16, v25, v16
	v_add_f32_e32 v25, v46, v21
	v_sub_f32_e32 v47, v29, v25
	v_sub_f32_e32 v29, v29, v47
	v_sub_f32_e32 v46, v25, v46
	v_sub_f32_e32 v25, v29, v25
	v_add_f32_e32 v16, v16, v25
	v_sub_f32_e32 v21, v46, v21
	v_add_f32_e32 v16, v21, v16
	v_add_f32_e32 v21, v30, v31
	v_add_f32_e32 v16, v47, v16
	v_sub_f32_e32 v25, v21, v30
	v_mul_f32_e32 v16, v27, v16
	v_sub_f32_e32 v25, v31, v25
	v_add_f32_e32 v16, v25, v16
	v_mul_f32_e32 v30, 0x3f317218, v23
	v_add_f32_e32 v25, v21, v16
	v_fma_f32 v31, v23, s6, -v30
	v_mul_f32_e32 v27, v25, v25
	v_fmac_f32_e32 v31, 0xb102e308, v23
	v_sub_f32_e32 v21, v25, v21
	v_fmamk_f32 v29, v27, 0x3e9b6dac, v177
	v_sub_f32_e32 v16, v16, v21
	v_add_f32_e32 v21, v30, v31
	v_fmaak_f32 v29, v27, v29, 0x3f2aaada
	v_sub_f32_e32 v23, v21, v30
	v_ldexp_f32 v30, v25, 1
	v_mul_f32_e32 v25, v25, v27
	v_mul_f32_e32 v25, v25, v29
	v_add_f32_e32 v27, v30, v25
	v_sub_f32_e32 v29, v27, v30
	v_ldexp_f32 v16, v16, 1
	v_sub_f32_e32 v25, v25, v29
	v_add_f32_e32 v16, v16, v25
	v_add_f32_e32 v25, v27, v16
	v_sub_f32_e32 v27, v25, v27
	v_sub_f32_e32 v16, v16, v27
	v_add_f32_e32 v27, v21, v25
	v_sub_f32_e32 v29, v27, v21
	v_sub_f32_e32 v30, v27, v29
	v_sub_f32_e32 v23, v31, v23
	v_sub_f32_e32 v21, v21, v30
	v_sub_f32_e32 v25, v25, v29
	v_add_f32_e32 v21, v25, v21
	v_add_f32_e32 v25, v23, v16
	v_sub_f32_e32 v29, v25, v23
	v_sub_f32_e32 v30, v25, v29
	v_sub_f32_e32 v23, v23, v30
	v_sub_f32_e32 v16, v16, v29
	v_add_f32_e32 v21, v25, v21
	v_add_f32_e32 v16, v16, v23
	v_add_f32_e32 v23, v27, v21
	v_sub_f32_e32 v25, v23, v27
	v_sub_f32_e32 v21, v21, v25
	v_add_f32_e32 v16, v16, v21
	s_mov_b32 s6, 0x7f800000
	v_add_f32_e32 v16, v23, v16
	v_cmp_neq_f32_e32 vcc, s6, v7
	s_mov_b32 s6, 0x33800000
	s_nop 0
	v_cndmask_b32_e32 v16, v184, v16, vcc
	v_cmp_ngt_f32_e32 vcc, -1.0, v7
	s_nop 1
	v_cndmask_b32_e32 v16, v185, v16, vcc
	v_cmp_neq_f32_e32 vcc, -1.0, v7
	s_nop 1
	v_cndmask_b32_e32 v16, v186, v16, vcc
	v_cmp_lt_f32_e64 vcc, |v7|, s6
	s_nop 1
	v_cndmask_b32_e32 v7, v16, v7, vcc
	v_sub_f32_e32 v30, v15, v7
	global_load_dword v15, v[32:33], off offset:64
	global_load_dword v16, v28, s[92:93]
	v_lshl_add_u32 v7, v189, 3, v188
	s_waitcnt vmcnt(0)
	v_add_f32_e32 v31, v15, v16
	ds_write_b64 v7, v[30:31] offset:33024
.LBB0_561:
	s_or_b64 exec, exec, s[4:5]
	s_movk_i32 s4, 0x80
	v_lshlrev_b32_e32 v30, 8, v13
	v_cmp_gt_u32_e64 s[4:5], s4, v189
	s_and_saveexec_b64 s[6:7], s[4:5]
	s_cbranch_execz .LBB0_563
	v_mov_b32_e32 v31, v17
	v_mov_b32_e32 v7, v17
	v_lshl_add_u64 v[32:33], v[0:1], 0, v[30:31]
	v_lshl_add_u64 v[32:33], v[32:33], 0, v[6:7]
	v_add_co_u32_e32 v32, vcc, 0x2000, v32
	s_nop 1
	v_addc_co_u32_e32 v33, vcc, 0, v33, vcc
	global_load_ushort v240, v[32:33], off
	global_load_ushort v241, v[32:33], off offset:1024
	v_lshl_add_u64 v[32:33], v[2:3], 0, v[30:31]
	v_lshl_add_u64 v[32:33], v[32:33], 0, v[6:7]
	v_add_co_u32_e32 v32, vcc, 0x2000, v32
	s_nop 1
	v_addc_co_u32_e32 v33, vcc, 0, v33, vcc
	global_load_ushort v242, v[32:33], off
	global_load_ushort v243, v[32:33], off offset:1024
	v_lshl_add_u64 v[32:33], v[34:35], 0, v[30:31]
	v_lshl_add_u64 v[32:33], v[32:33], 0, v[6:7]
	v_add_co_u32_e32 v32, vcc, 0x2000, v32
	s_nop 1
	v_addc_co_u32_e32 v33, vcc, 0, v33, vcc
	global_load_ushort v244, v[32:33], off
	global_load_ushort v245, v[32:33], off offset:1024
	v_lshl_add_u64 v[32:33], v[36:37], 0, v[30:31]
	v_lshl_add_u64 v[32:33], v[32:33], 0, v[6:7]
	v_add_co_u32_e32 v32, vcc, 0x2000, v32
	s_nop 1
	v_addc_co_u32_e32 v33, vcc, 0, v33, vcc
	global_load_ushort v246, v[32:33], off
	global_load_ushort v247, v[32:33], off offset:1024
	v_lshl_add_u64 v[32:33], v[38:39], 0, v[30:31]
	v_lshl_add_u64 v[32:33], v[32:33], 0, v[6:7]
	v_add_co_u32_e32 v32, vcc, 0x2000, v32
	s_nop 1
	v_addc_co_u32_e32 v33, vcc, 0, v33, vcc
	global_load_ushort v248, v[32:33], off
	global_load_ushort v249, v[32:33], off offset:1024
	v_lshl_add_u64 v[32:33], v[40:41], 0, v[30:31]
	v_lshl_add_u64 v[32:33], v[32:33], 0, v[6:7]
	v_add_co_u32_e32 v32, vcc, 0x2000, v32
	s_nop 1
	v_addc_co_u32_e32 v33, vcc, 0, v33, vcc
	global_load_ushort v250, v[32:33], off
	global_load_ushort v251, v[32:33], off offset:1024
	v_lshl_add_u64 v[32:33], v[42:43], 0, v[30:31]
	v_lshl_add_u64 v[32:33], v[32:33], 0, v[6:7]
	v_add_co_u32_e32 v32, vcc, 0x2000, v32
	s_nop 1
	v_addc_co_u32_e32 v33, vcc, 0, v33, vcc
	global_load_ushort v252, v[32:33], off
	global_load_ushort v253, v[32:33], off offset:1024
	v_lshl_add_u64 v[32:33], v[44:45], 0, v[30:31]
	v_lshl_add_u64 v[32:33], v[32:33], 0, v[6:7]
	v_add_co_u32_e32 v32, vcc, 0x2000, v32
	s_nop 1
	v_addc_co_u32_e32 v33, vcc, 0, v33, vcc
	global_load_ushort v254, v[32:33], off
	global_load_ushort v255, v[32:33], off offset:1024
	s_waitcnt vmcnt(0)
	v_lshlrev_b32_e32 v13, 16, v240
	v_mul_f32_e32 v13, 0x3db504f3, v13
	v_lshlrev_b32_e32 v15, 16, v241
	v_lshlrev_b32_e32 v16, 16, v242
	v_mul_f32_e32 v16, 0x3db504f3, v16
	ds_write2st64_b32 v19, v13, v16 offset1:2
	v_lshlrev_b32_e32 v13, 16, v243
	ds_write2st64_b32 v19, v15, v13 offset0:16 offset1:18
	v_lshlrev_b32_e32 v13, 16, v244
	v_mul_f32_e32 v13, 0x3db504f3, v13
	v_lshlrev_b32_e32 v15, 16, v245
	v_lshlrev_b32_e32 v16, 16, v246
	v_mul_f32_e32 v16, 0x3db504f3, v16
	ds_write2st64_b32 v19, v13, v16 offset0:4 offset1:6
	v_lshlrev_b32_e32 v13, 16, v247
	ds_write2st64_b32 v19, v15, v13 offset0:20 offset1:22
	v_lshlrev_b32_e32 v13, 16, v248
	v_mul_f32_e32 v13, 0x3db504f3, v13
	v_lshlrev_b32_e32 v15, 16, v249
	v_lshlrev_b32_e32 v16, 16, v250
	v_mul_f32_e32 v16, 0x3db504f3, v16
	ds_write2st64_b32 v19, v13, v16 offset0:8 offset1:10
	v_lshlrev_b32_e32 v13, 16, v251
	ds_write2st64_b32 v19, v15, v13 offset0:24 offset1:26
	v_lshlrev_b32_e32 v13, 16, v252
	v_mul_f32_e32 v13, 0x3db504f3, v13
	v_lshlrev_b32_e32 v15, 16, v253
	v_lshlrev_b32_e32 v7, 16, v254
	v_mul_f32_e32 v7, 0x3db504f3, v7
	ds_write2st64_b32 v19, v13, v7 offset0:12 offset1:14
	v_lshlrev_b32_e32 v7, 16, v255
	ds_write2st64_b32 v19, v15, v7 offset0:28 offset1:30
.LBB0_563:
	s_or_b64 exec, exec, s[6:7]
	v_lshlrev_b32_e32 v32, 1, v30
	v_mov_b32_e32 v33, v17
	v_lshl_add_u64 v[0:1], v[0:1], 0, v[32:33]
	v_mov_b32_e32 v7, v17
	v_lshl_add_u64 v[0:1], v[0:1], 0, v[6:7]
	v_add_co_u32_e32 v0, vcc, 0x2000, v0
	v_ashrrev_i32_e32 v27, 31, v26
	v_addc_co_u32_e32 v1, vcc, 0, v1, vcc
	global_load_ushort v240, v[0:1], off offset:2048
	v_lshlrev_b32_e32 v16, 2, v189
	s_mov_b32 s6, 0x10000
	v_lshlrev_b64 v[162:163], 7, v[26:27]
	v_mov_b32_e32 v164, 0
	v_lshl_add_u64 v[0:1], v[2:3], 0, v[32:33]
	v_lshl_add_u64 v[0:1], v[0:1], 0, v[6:7]
	v_add_co_u32_e32 v0, vcc, 0x2000, v0
	s_nop 1
	v_addc_co_u32_e32 v1, vcc, 0, v1, vcc
	global_load_ushort v241, v[0:1], off offset:2048
	v_lshl_add_u64 v[0:1], v[34:35], 0, v[32:33]
	v_lshl_add_u64 v[0:1], v[0:1], 0, v[6:7]
	v_add_co_u32_e32 v0, vcc, 0x2000, v0
	s_nop 1
	v_addc_co_u32_e32 v1, vcc, 0, v1, vcc
	global_load_ushort v243, v[0:1], off offset:2048
	v_lshl_add_u64 v[0:1], v[36:37], 0, v[32:33]
	v_lshl_add_u64 v[0:1], v[0:1], 0, v[6:7]
	v_add_co_u32_e32 v0, vcc, 0x2000, v0
	s_nop 1
	v_addc_co_u32_e32 v1, vcc, 0, v1, vcc
	global_load_ushort v244, v[0:1], off offset:2048
	v_lshl_add_u64 v[0:1], v[38:39], 0, v[32:33]
	v_lshl_add_u64 v[0:1], v[0:1], 0, v[6:7]
	v_add_co_u32_e32 v0, vcc, 0x2000, v0
	s_nop 1
	v_addc_co_u32_e32 v1, vcc, 0, v1, vcc
	global_load_ushort v246, v[0:1], off offset:2048
	v_lshl_add_u64 v[0:1], v[40:41], 0, v[32:33]
	v_lshl_add_u64 v[0:1], v[0:1], 0, v[6:7]
	v_add_co_u32_e32 v0, vcc, 0x2000, v0
	s_nop 1
	v_addc_co_u32_e32 v1, vcc, 0, v1, vcc
	global_load_ushort v247, v[0:1], off offset:2048
	v_lshl_add_u64 v[0:1], v[42:43], 0, v[32:33]
	v_lshl_add_u64 v[0:1], v[0:1], 0, v[6:7]
	v_add_co_u32_e32 v0, vcc, 0x2000, v0
	s_nop 1
	v_addc_co_u32_e32 v1, vcc, 0, v1, vcc
	global_load_ushort v249, v[0:1], off offset:2048
	v_lshl_add_u64 v[0:1], v[44:45], 0, v[32:33]
	v_lshl_add_u64 v[0:1], v[0:1], 0, v[6:7]
	v_add_co_u32_e32 v0, vcc, 0x2000, v0
	s_nop 1
	v_addc_co_u32_e32 v1, vcc, 0, v1, vcc
	global_load_ushort v250, v[0:1], off offset:2048
	s_waitcnt vmcnt(0)
	v_lshlrev_b32_e32 v13, 16, v240
	v_lshlrev_b32_e32 v242, 16, v241
	ds_write2st64_b32 v19, v13, v242 offset0:32 offset1:36
	v_lshlrev_b32_e32 v2, 16, v243
	v_lshlrev_b32_e32 v245, 16, v244
	ds_write2st64_b32 v19, v2, v245 offset0:40 offset1:44
	v_lshlrev_b32_e32 v2, 16, v246
	v_lshlrev_b32_e32 v248, 16, v247
	ds_write2st64_b32 v19, v2, v248 offset0:48 offset1:52
	v_lshlrev_b32_e32 v2, 16, v249
	v_lshlrev_b32_e32 v0, 16, v250
	ds_write2st64_b32 v19, v2, v0 offset0:56 offset1:60
	v_lshlrev_b64 v[0:1], 17, v[26:27]
	v_lshl_add_u64 v[0:1], s[72:73], 0, v[0:1]
	v_lshl_add_u64 v[0:1], v[0:1], 0, v[16:17]
	v_add_co_u32_e32 v2, vcc, s47, v0
	global_load_dword v40, v[0:1], off nt
	global_load_dword v41, v[0:1], off offset:1024 nt
	global_load_dword v38, v[0:1], off offset:2048 nt
	global_load_dword v39, v[0:1], off offset:3072 nt
	v_addc_co_u32_e32 v3, vcc, 0, v1, vcc
	v_add_co_u32_e32 v46, vcc, s27, v0
	s_nop 1
	v_addc_co_u32_e32 v47, vcc, 0, v1, vcc
	global_load_dword v44, v[46:47], off offset:-4096 nt
	global_load_dword v45, v[2:3], off offset:1024 nt
	global_load_dword v42, v[2:3], off offset:2048 nt
	global_load_dword v43, v[2:3], off offset:3072 nt
	global_load_dword v36, v[46:47], off nt
	global_load_dword v37, v[46:47], off offset:1024 nt
	global_load_dword v34, v[46:47], off offset:2048 nt
	global_load_dword v35, v[46:47], off offset:3072 nt
	v_add_co_u32_e32 v2, vcc, s39, v0
	s_nop 1
	v_addc_co_u32_e32 v3, vcc, 0, v1, vcc
	v_add_co_u32_e32 v54, vcc, s50, v0
	s_nop 1
	v_addc_co_u32_e32 v55, vcc, 0, v1, vcc
	global_load_dword v46, v[54:55], off offset:-4096 nt
	global_load_dword v47, v[2:3], off offset:1024 nt
	global_load_dword v52, v[2:3], off offset:2048 nt
	global_load_dword v53, v[2:3], off offset:3072 nt
	global_load_dword v50, v[54:55], off nt
	global_load_dword v51, v[54:55], off offset:1024 nt
	global_load_dword v48, v[54:55], off offset:2048 nt
	global_load_dword v49, v[54:55], off offset:3072 nt
	v_add_co_u32_e32 v2, vcc, s51, v0
	s_nop 1
	v_addc_co_u32_e32 v3, vcc, 0, v1, vcc
	v_add_co_u32_e32 v62, vcc, s82, v0
	s_nop 1
	v_addc_co_u32_e32 v63, vcc, 0, v1, vcc
	global_load_dword v60, v[62:63], off offset:-4096 nt
	global_load_dword v61, v[2:3], off offset:1024 nt
	global_load_dword v58, v[2:3], off offset:2048 nt
	global_load_dword v59, v[2:3], off offset:3072 nt
	global_load_dword v56, v[62:63], off nt
	global_load_dword v57, v[62:63], off offset:1024 nt
	global_load_dword v54, v[62:63], off offset:2048 nt
	global_load_dword v55, v[62:63], off offset:3072 nt
	v_add_co_u32_e32 v2, vcc, s83, v0
	s_nop 1
	v_addc_co_u32_e32 v3, vcc, 0, v1, vcc
	v_add_co_u32_e32 v66, vcc, s96, v0
	s_nop 1
	v_addc_co_u32_e32 v67, vcc, 0, v1, vcc
	global_load_dword v62, v[66:67], off offset:-4096 nt
	global_load_dword v63, v[2:3], off offset:1024 nt
	global_load_dword v64, v[2:3], off offset:2048 nt
	global_load_dword v65, v[2:3], off offset:3072 nt
	global_load_dword v72, v[66:67], off nt
	global_load_dword v73, v[66:67], off offset:1024 nt
	global_load_dword v70, v[66:67], off offset:2048 nt
	global_load_dword v71, v[66:67], off offset:3072 nt
	v_add_co_u32_e32 v2, vcc, s97, v0
	s_nop 1
	v_addc_co_u32_e32 v3, vcc, 0, v1, vcc
	v_add_co_u32_e32 v78, vcc, s17, v0
	s_nop 1
	v_addc_co_u32_e32 v79, vcc, 0, v1, vcc
	global_load_dword v76, v[78:79], off offset:-4096 nt
	global_load_dword v77, v[2:3], off offset:1024 nt
	global_load_dword v74, v[2:3], off offset:2048 nt
	global_load_dword v75, v[2:3], off offset:3072 nt
	global_load_dword v68, v[78:79], off nt
	global_load_dword v69, v[78:79], off offset:1024 nt
	global_load_dword v66, v[78:79], off offset:2048 nt
	global_load_dword v67, v[78:79], off offset:3072 nt
	v_add_co_u32_e32 v2, vcc, s10, v0
	s_nop 1
	v_addc_co_u32_e32 v3, vcc, 0, v1, vcc
	v_add_co_u32_e32 v86, vcc, s11, v0
	s_nop 1
	v_addc_co_u32_e32 v87, vcc, 0, v1, vcc
	global_load_dword v84, v[86:87], off offset:-4096 nt
	global_load_dword v85, v[2:3], off offset:1024 nt
	global_load_dword v82, v[2:3], off offset:2048 nt
	global_load_dword v83, v[2:3], off offset:3072 nt
	global_load_dword v80, v[86:87], off nt
	global_load_dword v81, v[86:87], off offset:1024 nt
	global_load_dword v78, v[86:87], off offset:2048 nt
	global_load_dword v79, v[86:87], off offset:3072 nt
	v_add_co_u32_e32 v2, vcc, s42, v0
	s_nop 1
	v_addc_co_u32_e32 v3, vcc, 0, v1, vcc
	v_add_co_u32_e32 v88, vcc, s18, v0
	s_nop 1
	v_addc_co_u32_e32 v89, vcc, 0, v1, vcc
	global_load_dword v86, v[88:89], off offset:-4096 nt
	global_load_dword v87, v[2:3], off offset:1024 nt
	global_load_dword v92, v[2:3], off offset:2048 nt
	global_load_dword v93, v[2:3], off offset:3072 nt
	global_load_dword v96, v[88:89], off nt
	global_load_dword v97, v[88:89], off offset:1024 nt
	global_load_dword v94, v[88:89], off offset:2048 nt
	global_load_dword v95, v[88:89], off offset:3072 nt
	v_add_co_u32_e32 v2, vcc, s19, v0
	s_nop 1
	v_addc_co_u32_e32 v3, vcc, 0, v1, vcc
	v_add_co_u32_e32 v102, vcc, s6, v0
	s_mov_b32 s6, 0x11000
	s_nop 0
	v_addc_co_u32_e32 v103, vcc, 0, v1, vcc
	global_load_dword v100, v[102:103], off offset:-4096 nt
	global_load_dword v101, v[2:3], off offset:1024 nt
	global_load_dword v98, v[2:3], off offset:2048 nt
	global_load_dword v99, v[2:3], off offset:3072 nt
	global_load_dword v90, v[102:103], off nt
	global_load_dword v91, v[102:103], off offset:1024 nt
	global_load_dword v88, v[102:103], off offset:2048 nt
	global_load_dword v89, v[102:103], off offset:3072 nt
	v_add_co_u32_e32 v2, vcc, s6, v0
	s_mov_b32 s6, 0x12000
	s_nop 0
	v_addc_co_u32_e32 v3, vcc, 0, v1, vcc
	v_add_co_u32_e32 v110, vcc, s6, v0
	s_mov_b32 s6, 0x13000
	s_nop 0
	v_addc_co_u32_e32 v111, vcc, 0, v1, vcc
	global_load_dword v108, v[110:111], off offset:-4096 nt
	global_load_dword v109, v[2:3], off offset:1024 nt
	global_load_dword v106, v[2:3], off offset:2048 nt
	global_load_dword v107, v[2:3], off offset:3072 nt
	global_load_dword v104, v[110:111], off nt
	global_load_dword v105, v[110:111], off offset:1024 nt
	global_load_dword v102, v[110:111], off offset:2048 nt
	global_load_dword v103, v[110:111], off offset:3072 nt
	v_add_co_u32_e32 v2, vcc, s6, v0
	s_mov_b32 s6, 0x14000
	s_nop 0
	v_addc_co_u32_e32 v3, vcc, 0, v1, vcc
	v_add_co_u32_e32 v118, vcc, s6, v0
	s_mov_b32 s6, 0x15000
	s_nop 0
	v_addc_co_u32_e32 v119, vcc, 0, v1, vcc
	global_load_dword v110, v[118:119], off offset:-4096 nt
	global_load_dword v111, v[2:3], off offset:1024 nt
	global_load_dword v116, v[2:3], off offset:2048 nt
	global_load_dword v117, v[2:3], off offset:3072 nt
	global_load_dword v114, v[118:119], off nt
	global_load_dword v115, v[118:119], off offset:1024 nt
	global_load_dword v112, v[118:119], off offset:2048 nt
	global_load_dword v113, v[118:119], off offset:3072 nt
	v_add_co_u32_e32 v2, vcc, s6, v0
	s_mov_b32 s6, 0x16000
	s_nop 0
	v_addc_co_u32_e32 v3, vcc, 0, v1, vcc
	v_add_co_u32_e32 v126, vcc, s6, v0
	s_mov_b32 s6, 0x17000
	s_nop 0
	v_addc_co_u32_e32 v127, vcc, 0, v1, vcc
	global_load_dword v124, v[126:127], off offset:-4096 nt
	global_load_dword v125, v[2:3], off offset:1024 nt
	global_load_dword v122, v[2:3], off offset:2048 nt
	global_load_dword v123, v[2:3], off offset:3072 nt
	global_load_dword v120, v[126:127], off nt
	global_load_dword v121, v[126:127], off offset:1024 nt
	global_load_dword v118, v[126:127], off offset:2048 nt
	global_load_dword v119, v[126:127], off offset:3072 nt
	v_add_co_u32_e32 v2, vcc, s6, v0
	s_mov_b32 s6, 0x18000
	s_nop 0
	v_addc_co_u32_e32 v3, vcc, 0, v1, vcc
	v_add_co_u32_e32 v128, vcc, s6, v0
	s_mov_b32 s6, 0x19000
	s_nop 0
	v_addc_co_u32_e32 v129, vcc, 0, v1, vcc
	global_load_dword v126, v[128:129], off offset:-4096 nt
	global_load_dword v127, v[2:3], off offset:1024 nt
	global_load_dword v132, v[2:3], off offset:2048 nt
	global_load_dword v133, v[2:3], off offset:3072 nt
	global_load_dword v136, v[128:129], off nt
	global_load_dword v137, v[128:129], off offset:1024 nt
	global_load_dword v134, v[128:129], off offset:2048 nt
	global_load_dword v135, v[128:129], off offset:3072 nt
	v_add_co_u32_e32 v2, vcc, s6, v0
	s_mov_b32 s6, 0x1a000
	s_nop 0
	v_addc_co_u32_e32 v3, vcc, 0, v1, vcc
	v_add_co_u32_e32 v142, vcc, s6, v0
	s_mov_b32 s6, 0x1b000
	s_nop 0
	v_addc_co_u32_e32 v143, vcc, 0, v1, vcc
	global_load_dword v140, v[142:143], off offset:-4096 nt
	global_load_dword v141, v[2:3], off offset:1024 nt
	global_load_dword v138, v[2:3], off offset:2048 nt
	global_load_dword v139, v[2:3], off offset:3072 nt
	global_load_dword v130, v[142:143], off nt
	global_load_dword v131, v[142:143], off offset:1024 nt
	global_load_dword v128, v[142:143], off offset:2048 nt
	global_load_dword v129, v[142:143], off offset:3072 nt
	v_add_co_u32_e32 v2, vcc, s6, v0
	s_nop 1
	v_addc_co_u32_e32 v3, vcc, 0, v1, vcc
	v_add_co_u32_e32 v150, vcc, s45, v0
	s_nop 1
	v_addc_co_u32_e32 v151, vcc, 0, v1, vcc
	global_load_dword v148, v[150:151], off offset:-4096 nt
	global_load_dword v149, v[2:3], off offset:1024 nt
	global_load_dword v146, v[2:3], off offset:2048 nt
	global_load_dword v147, v[2:3], off offset:3072 nt
	global_load_dword v144, v[150:151], off nt
	global_load_dword v145, v[150:151], off offset:1024 nt
	global_load_dword v142, v[150:151], off offset:2048 nt
	global_load_dword v143, v[150:151], off offset:3072 nt
	v_add_co_u32_e32 v2, vcc, s46, v0
	s_nop 1
	v_addc_co_u32_e32 v3, vcc, 0, v1, vcc
	v_add_co_u32_e32 v158, vcc, s14, v0
	s_nop 1
	v_addc_co_u32_e32 v159, vcc, 0, v1, vcc
	global_load_dword v150, v[158:159], off offset:-4096 nt
	global_load_dword v151, v[2:3], off offset:1024 nt
	global_load_dword v152, v[2:3], off offset:2048 nt
	global_load_dword v153, v[2:3], off offset:3072 nt
	global_load_dword v154, v[158:159], off nt
	global_load_dword v155, v[158:159], off offset:1024 nt
	global_load_dword v156, v[158:159], off offset:2048 nt
	global_load_dword v157, v[158:159], off offset:3072 nt
	v_add_co_u32_e32 v0, vcc, 0x1f000, v0
	s_nop 1
	v_addc_co_u32_e32 v1, vcc, 0, v1, vcc
	global_load_dword v158, v[0:1], off nt
	global_load_dword v159, v[0:1], off offset:1024 nt
	global_load_dword v160, v[0:1], off offset:2048 nt
	global_load_dword v161, v[0:1], off offset:3072 nt
	s_and_saveexec_b64 s[6:7], s[4:5]
	s_cbranch_execz .LBB0_565
	v_lshl_add_u64 v[0:1], v[162:163], 2, s[74:75]
	v_lshl_add_u64 v[0:1], v[0:1], 0, v[16:17]
	global_load_dword v164, v[0:1], off

.LBB0_608:
	v_mov_b32_e32 v13, v176
	v_mov_b32_e32 v29, v17
	v_ashrrev_i32_e32 v0, 7, v13
	v_lshl_add_u32 v30, s44, 2, v0
	v_mul_lo_u32 v0, v0, s82
	v_and_b32_e32 v4, -8, v30
	v_and_b32_e32 v9, 7, v30
	v_add_u32_e32 v156, 0, v0
	v_add_u32_e32 v26, 0x2000, v4
	v_mov_b64_e32 v[0:1], s[30:31]
	v_and_b32_e32 v72, 0x7f, v13
	v_mad_i64_i32 v[2:3], s[4:5], v26, s37, v[0:1]
	v_lshlrev_b32_e32 v16, 8, v9
	v_lshl_add_u64 v[2:3], v[2:3], 0, v[16:17]
	v_lshlrev_b32_e32 v28, 1, v72
	v_lshl_add_u64 v[2:3], v[2:3], 0, v[28:29]
	v_add_co_u32_e32 v2, vcc, s47, v2
	v_add_u32_e32 v24, 0x2001, v4
	v_addc_co_u32_e32 v3, vcc, 0, v3, vcc
	global_load_ushort v240, v[2:3], off offset:2048
	v_lshl_add_u32 v155, v72, 2, v156
	v_add_u32_e32 v20, 0x2002, v4
	v_add_u32_e32 v14, 0x2003, v4
	v_add_u32_e32 v22, 0x2004, v4
	v_add_u32_e32 v12, 0x2005, v4
	v_add_u32_e32 v10, 0x2006, v4
	v_add_u32_e32 v8, 0x2007, v4
	v_lshlrev_b32_e32 v157, 7, v9
	v_or_b32_e32 v15, v157, v72
	v_bfe_u32 v11, v13, 6, 1
	v_and_b32_e32 v13, 63, v13
	v_lshl_add_u32 v162, v11, 6, v156
	v_mad_i64_i32 v[2:3], s[4:5], v24, s37, v[0:1]
	v_lshl_add_u64 v[2:3], v[2:3], 0, v[16:17]
	v_lshl_add_u64 v[2:3], v[2:3], 0, v[28:29]
	v_add_co_u32_e32 v2, vcc, s47, v2
	s_nop 1
	v_addc_co_u32_e32 v3, vcc, 0, v3, vcc
	global_load_ushort v241, v[2:3], off offset:2048
	v_mad_i64_i32 v[2:3], s[4:5], v20, s37, v[0:1]
	v_lshl_add_u64 v[2:3], v[2:3], 0, v[16:17]
	v_lshl_add_u64 v[2:3], v[2:3], 0, v[28:29]
	v_add_co_u32_e32 v2, vcc, s47, v2
	s_nop 1
	v_addc_co_u32_e32 v3, vcc, 0, v3, vcc
	global_load_ushort v243, v[2:3], off offset:2048
	v_mad_i64_i32 v[2:3], s[4:5], v14, s37, v[0:1]
	v_lshl_add_u64 v[2:3], v[2:3], 0, v[16:17]
	v_lshl_add_u64 v[2:3], v[2:3], 0, v[28:29]
	v_add_co_u32_e32 v2, vcc, s47, v2
	s_nop 1
	v_addc_co_u32_e32 v3, vcc, 0, v3, vcc
	global_load_ushort v244, v[2:3], off offset:2048
	v_mad_i64_i32 v[2:3], s[4:5], v22, s37, v[0:1]
	v_lshl_add_u64 v[2:3], v[2:3], 0, v[16:17]
	v_lshl_add_u64 v[2:3], v[2:3], 0, v[28:29]
	v_add_co_u32_e32 v2, vcc, s47, v2
	s_nop 1
	v_addc_co_u32_e32 v3, vcc, 0, v3, vcc
	global_load_ushort v246, v[2:3], off offset:2048
	v_mad_i64_i32 v[2:3], s[4:5], v12, s37, v[0:1]
	v_lshl_add_u64 v[2:3], v[2:3], 0, v[16:17]
	v_lshl_add_u64 v[2:3], v[2:3], 0, v[28:29]
	v_add_co_u32_e32 v2, vcc, s47, v2
	s_nop 1
	v_addc_co_u32_e32 v3, vcc, 0, v3, vcc
	global_load_ushort v247, v[2:3], off offset:2048
	v_mad_i64_i32 v[2:3], s[4:5], v10, s37, v[0:1]
	v_lshl_add_u64 v[2:3], v[2:3], 0, v[16:17]
	v_lshl_add_u64 v[2:3], v[2:3], 0, v[28:29]
	v_mad_i64_i32 v[0:1], s[4:5], v8, s37, v[0:1]
	v_add_co_u32_e32 v2, vcc, s47, v2
	v_lshl_add_u64 v[0:1], v[0:1], 0, v[16:17]
	v_addc_co_u32_e32 v3, vcc, 0, v3, vcc
	v_lshl_add_u64 v[0:1], v[0:1], 0, v[28:29]
	v_add_co_u32_e32 v0, vcc, s47, v0
	global_load_ushort v249, v[2:3], off offset:2048
	v_addc_co_u32_e32 v1, vcc, 0, v1, vcc
	global_load_ushort v250, v[0:1], off offset:2048
	v_lshlrev_b32_e32 v16, 2, v15
	global_load_dword v56, v16, s[84:85]
	s_waitcnt vmcnt(0)
	v_lshlrev_b32_e32 v5, 16, v240
	v_lshlrev_b32_e32 v242, 16, v241
	ds_write2st64_b32 v155, v5, v242 offset0:64 offset1:66
	v_lshlrev_b32_e32 v5, 16, v243
	v_lshlrev_b32_e32 v245, 16, v244
	ds_write2st64_b32 v155, v5, v245 offset0:68 offset1:70
	v_lshlrev_b32_e32 v5, 16, v246
	v_lshlrev_b32_e32 v248, 16, v247
	ds_write2st64_b32 v155, v5, v248 offset0:72 offset1:74
	v_lshlrev_b32_e32 v2, 16, v249
	v_lshlrev_b32_e32 v0, 16, v250
	ds_write2st64_b32 v155, v2, v0 offset0:76 offset1:78
	v_ashrrev_i32_e32 v0, 3, v30
	v_lshl_add_u32 v23, v0, 1, v0
	v_lshl_add_u64 v[0:1], s[68:69], 0, v[16:17]
	v_mad_i64_i32 v[2:3], s[4:5], v23, s39, v[0:1]
	v_add_u32_e32 v19, 1, v23
	v_add_u32_e32 v21, 2, v23
	global_load_dword v58, v[2:3], off
	v_mad_i64_i32 v[2:3], s[4:5], v19, s39, v[0:1]
	v_mad_i64_i32 v[0:1], s[4:5], v21, s39, v[0:1]
	global_load_dword v46, v[2:3], off
	global_load_dword v59, v[0:1], off
	v_lshlrev_b32_e32 v0, 1, v15
	v_mov_b32_e32 v1, v17
	v_lshl_add_u64 v[4:5], s[30:31], 0, v[0:1]
	v_mad_i64_i32 v[6:7], s[4:5], v26, s37, v[4:5]
	global_load_ushort v0, v[6:7], off
	v_mad_i64_i32 v[36:37], s[4:5], v24, s37, v[4:5]
	v_mad_i64_i32 v[38:39], s[4:5], v20, s37, v[4:5]
	v_mad_i64_i32 v[48:49], s[4:5], v14, s37, v[4:5]
	v_mad_i64_i32 v[60:61], s[4:5], v22, s37, v[4:5]
	v_mad_i64_i32 v[62:63], s[4:5], v12, s37, v[4:5]
	v_mad_i64_i32 v[64:65], s[4:5], v10, s37, v[4:5]
	v_mad_i64_i32 v[66:67], s[4:5], v8, s37, v[4:5]
	v_lshl_add_u64 v[4:5], s[84:85], 0, v[16:17]
	v_add_co_u32_e32 v32, vcc, s39, v4
	v_or_b32_e32 v16, 0x1000, v16
	s_nop 0
	v_addc_co_u32_e32 v33, vcc, 0, v5, vcc
	global_load_dword v57, v[32:33], off
	v_add_co_u32_e32 v32, vcc, s82, v4
	v_or_b32_e32 v15, 0x800, v15
	s_nop 0
	v_addc_co_u32_e32 v33, vcc, 0, v5, vcc
	v_add_co_u32_e32 v4, vcc, s97, v4
	global_load_dword v32, v[32:33], off
	s_nop 0
	v_addc_co_u32_e32 v5, vcc, 0, v5, vcc
	global_load_dword v34, v[4:5], off
	v_lshl_add_u64 v[4:5], s[68:69], 0, v[16:17]
	v_mad_i64_i32 v[40:41], s[4:5], v23, s39, v[4:5]
	global_load_dword v50, v[40:41], off
	v_mad_i64_i32 v[40:41], s[4:5], v19, s39, v[4:5]
	v_mad_i64_i32 v[4:5], s[4:5], v21, s39, v[4:5]
	global_load_dword v54, v[40:41], off
	global_load_ushort v1, v[62:63], off
	global_load_ushort v3, v[66:67], off
	global_load_ushort v2, v[64:65], off
	s_waitcnt vmcnt(8)
	v_lshlrev_b32_e32 v52, 16, v0
	global_load_ushort v0, v[36:37], off
	s_waitcnt vmcnt(8)
	v_pk_mul_f32 v[68:69], v[58:59], v[56:57]
	s_waitcnt vmcnt(3)
	v_lshlrev_b32_e32 v1, 16, v1
	s_waitcnt vmcnt(2)
	v_lshlrev_b32_e32 v3, 16, v3
	s_waitcnt vmcnt(1)
	v_lshlrev_b32_e32 v2, 16, v2
	s_waitcnt vmcnt(0)
	v_lshlrev_b32_e32 v53, 16, v0
	global_load_ushort v0, v[38:39], off
	s_waitcnt vmcnt(0)
	v_lshlrev_b32_e32 v42, 16, v0
	global_load_ushort v0, v[48:49], off
	s_waitcnt vmcnt(0)
	v_lshlrev_b32_e32 v43, 16, v0
	global_load_ushort v0, v[60:61], off
	global_load_dword v51, v[4:5], off
	s_nop 0
	global_load_ushort v4, v[6:7], off offset:2048
	global_load_ushort v5, v[62:63], off offset:2048
	s_waitcnt vmcnt(3)
	v_lshlrev_b32_e32 v0, 16, v0
	s_waitcnt vmcnt(1)
	v_lshlrev_b32_e32 v44, 16, v4
	global_load_ushort v4, v[36:37], off offset:2048
	global_load_ushort v6, v[64:65], off offset:2048
	s_waitcnt vmcnt(2)
	v_lshlrev_b32_e32 v5, 16, v5
	global_load_ushort v7, v[66:67], off offset:2048
	v_pk_mov_b32 v[66:67], v[58:59], v[52:53] op_sel:[1,0]
	v_mov_b32_e32 v58, v59
	v_mov_b32_e32 v59, v53
	s_waitcnt vmcnt(2)
	v_lshlrev_b32_e32 v45, 16, v4
	global_load_ushort v4, v[38:39], off offset:2048
	v_lshl_add_u64 v[38:39], s[84:85], 0, v[16:17]
	v_add_co_u32_e32 v36, vcc, s39, v38
	v_pk_mov_b32 v[70:71], v[50:51], v[44:45] op_sel:[1,0]
	s_nop 0
	v_addc_co_u32_e32 v37, vcc, 0, v39, vcc
	s_waitcnt vmcnt(2)
	v_lshlrev_b32_e32 v6, 16, v6
	s_waitcnt vmcnt(1)
	v_lshlrev_b32_e32 v7, 16, v7
	s_waitcnt vmcnt(0)
	v_lshlrev_b32_e32 v40, 16, v4
	global_load_ushort v4, v[48:49], off offset:2048
	s_waitcnt vmcnt(0)
	v_lshlrev_b32_e32 v41, 16, v4
	global_load_dword v48, v16, s[84:85]
	global_load_dword v49, v[36:37], off
	v_lshlrev_b32_e32 v16, 2, v15
	global_load_ushort v4, v[60:61], off offset:2048
	v_lshl_add_u64 v[60:61], s[68:69], 0, v[16:17]
	v_mad_i64_i32 v[62:63], s[4:5], v19, s39, v[60:61]
	global_load_dword v25, v[62:63], off
	v_mad_i64_i32 v[62:63], s[4:5], v21, s39, v[60:61]
	v_mad_i64_i32 v[60:61], s[4:5], v23, s39, v[60:61]
	global_load_dword v27, v[62:63], off
	global_load_dword v23, v[60:61], off
	v_lshlrev_b32_e32 v62, 1, v15
	v_mov_b32_e32 v63, v17
	v_lshl_add_u64 v[62:63], s[30:31], 0, v[62:63]
	v_mad_i64_i32 v[64:65], s[4:5], v26, s37, v[62:63]
	global_load_ushort v15, v[64:65], off
	v_mad_i64_i32 v[64:65], s[4:5], v24, s37, v[62:63]
	v_add_co_u32_e32 v36, vcc, s82, v38
	s_waitcnt vmcnt(5)
	v_pk_mul_f32 v[74:75], v[50:51], v[48:49]
	v_addc_co_u32_e32 v37, vcc, 0, v39, vcc
	v_add_co_u32_e32 v38, vcc, s97, v38
	global_load_dword v36, v[36:37], off
	s_nop 0
	v_addc_co_u32_e32 v39, vcc, 0, v39, vcc
	global_load_dword v38, v[38:39], off
	v_mov_b32_e32 v50, v51
	v_mov_b32_e32 v51, v45
	s_waitcnt vmcnt(6)
	v_lshlrev_b32_e32 v4, 16, v4
	s_waitcnt vmcnt(2)
	v_lshlrev_b32_e32 v29, 16, v15
	global_load_ushort v15, v[64:65], off
	v_mad_i64_i32 v[64:65], s[4:5], v20, s37, v[62:63]
	s_waitcnt vmcnt(0)
	v_lshlrev_b32_e32 v31, 16, v15
	global_load_ushort v15, v[64:65], off
	v_mad_i64_i32 v[64:65], s[4:5], v14, s37, v[62:63]
	s_waitcnt vmcnt(0)
	v_lshlrev_b32_e32 v33, 16, v15
	global_load_ushort v15, v[64:65], off
	v_mad_i64_i32 v[64:65], s[4:5], v22, s37, v[62:63]
	s_waitcnt vmcnt(0)
	v_lshlrev_b32_e32 v21, 16, v15
	global_load_ushort v15, v[64:65], off
	v_mad_i64_i32 v[64:65], s[4:5], v12, s37, v[62:63]
	global_load_ushort v19, v[64:65], off
	v_mad_i64_i32 v[64:65], s[4:5], v10, s37, v[62:63]
	v_mad_i64_i32 v[62:63], s[4:5], v8, s37, v[62:63]
	global_load_ushort v35, v[64:65], off
	global_load_ushort v37, v[62:63], off
	v_lshl_add_u64 v[62:63], s[84:85], 0, v[16:17]
	v_add_co_u32_e32 v64, vcc, s39, v62
	global_load_dword v16, v16, s[84:85]
	s_nop 0
	v_addc_co_u32_e32 v65, vcc, 0, v63, vcc
	global_load_dword v39, v[64:65], off
	v_add_co_u32_e32 v64, vcc, s82, v62
	v_cmp_eq_u32_e64 s[4:5], 0, v13
	s_nop 0
	v_addc_co_u32_e32 v65, vcc, 0, v63, vcc
	v_add_co_u32_e32 v62, vcc, s97, v62
	global_load_dword v47, v[64:65], off
	s_nop 0
	v_addc_co_u32_e32 v63, vcc, 0, v63, vcc
	global_load_dword v55, v[62:63], off
	v_mov_b32_e32 v62, v57
	v_mov_b32_e32 v63, v56
	v_pk_mov_b32 v[64:65], v[44:45], v[40:41] op_sel:[1,0]
	s_waitcnt vmcnt(7)
	v_lshlrev_b32_e32 v15, 16, v15
	s_waitcnt vmcnt(6)
	v_lshlrev_b32_e32 v19, 16, v19
	s_waitcnt vmcnt(5)
	v_lshlrev_b32_e32 v35, 16, v35
	s_waitcnt vmcnt(4)
	v_lshlrev_b32_e32 v37, 16, v37
	s_waitcnt vmcnt(3)
	v_mul_f32_e32 v23, v16, v23
	s_waitcnt vmcnt(2)
	v_fmac_f32_e32 v23, v25, v39
	s_waitcnt vmcnt(1)
	v_fmac_f32_e32 v23, v27, v47
	s_waitcnt vmcnt(0)
	v_fmac_f32_e32 v23, v55, v29
	v_mul_f32_e32 v60, 0xbfb8aa3b, v23
	v_exp_f32_e32 v60, v60
	s_nop 0
	v_add_f32_e32 v60, 1.0, v60
	v_rcp_f32_e32 v60, v60
	s_nop 0
	v_mul_f32_e32 v23, v23, v60
	v_mul_f32_e32 v60, v27, v39
	v_fmac_f32_e32 v60, v25, v16
	v_fmac_f32_e32 v60, v47, v29
	v_fmac_f32_e32 v60, v55, v31
	v_mul_f32_e32 v25, 0xbfb8aa3b, v60
	v_exp_f32_e32 v25, v25
	s_nop 0
	v_add_f32_e32 v25, 1.0, v25
	v_rcp_f32_e32 v25, v25
	s_nop 0
	v_mul_f32_e32 v25, v60, v25
	ds_write2st64_b32 v155, v23, v25 offset0:32 offset1:34
	v_mul_f32_e32 v23, v39, v29
	v_fmac_f32_e32 v23, v27, v16
	v_fmac_f32_e32 v23, v47, v31
	v_fmac_f32_e32 v23, v55, v33
	v_mul_f32_e32 v25, 0xbfb8aa3b, v23
	v_exp_f32_e32 v25, v25
	v_pk_mov_b32 v[60:61], v[52:53], v[42:43] op_sel:[1,0]
	v_add_f32_e32 v25, 1.0, v25
	v_rcp_f32_e32 v25, v25
	s_nop 0
	v_mul_f32_e32 v23, v23, v25
	v_mul_f32_e32 v25, v39, v31
	v_fmac_f32_e32 v25, v16, v29
	v_fmac_f32_e32 v25, v47, v33
	v_fmac_f32_e32 v25, v55, v21
	v_mul_f32_e32 v27, 0xbfb8aa3b, v25
	v_exp_f32_e32 v27, v27
	s_nop 0
	v_add_f32_e32 v27, 1.0, v27
	v_rcp_f32_e32 v27, v27
	s_nop 0
	v_mul_f32_e32 v25, v25, v27
	ds_write2st64_b32 v155, v23, v25 offset0:36 offset1:38
	v_mul_f32_e32 v23, v39, v33
	v_fmac_f32_e32 v23, v16, v31
	v_fmac_f32_e32 v23, v47, v21
	v_fmac_f32_e32 v23, v55, v15
	v_mul_f32_e32 v25, 0xbfb8aa3b, v23
	v_exp_f32_e32 v25, v25
	s_nop 0
	v_add_f32_e32 v25, 1.0, v25
	v_rcp_f32_e32 v25, v25
	s_nop 0
	v_mul_f32_e32 v23, v23, v25
	v_mul_f32_e32 v25, v39, v21
	v_fmac_f32_e32 v25, v16, v33
	v_fmac_f32_e32 v25, v47, v15
	v_fmac_f32_e32 v25, v55, v19
	v_mul_f32_e32 v27, 0xbfb8aa3b, v25
	v_exp_f32_e32 v27, v27
	s_nop 0
	v_add_f32_e32 v27, 1.0, v27
	v_rcp_f32_e32 v27, v27
	s_nop 0
	v_mul_f32_e32 v25, v25, v27
	ds_write2st64_b32 v155, v23, v25 offset0:40 offset1:42
	v_mul_f32_e32 v23, v39, v15
	v_fmac_f32_e32 v23, v16, v21
	v_fmac_f32_e32 v23, v47, v19
	v_mul_f32_e32 v19, v39, v19
	v_fmac_f32_e32 v19, v16, v15
	v_fmac_f32_e32 v19, v47, v35
	v_fmac_f32_e32 v23, v55, v35
	v_fmac_f32_e32 v19, v55, v37
	v_mul_f32_e32 v21, 0xbfb8aa3b, v23
	v_mul_f32_e32 v15, 0xbfb8aa3b, v19
	v_exp_f32_e32 v21, v21
	v_exp_f32_e32 v15, v15
	v_xor_b32_e32 v16, 32, v187
	v_pk_fma_f32 v[46:47], v[46:47], v[62:63], v[68:69] op_sel_hi:[0,1,1]
	v_add_f32_e32 v21, 1.0, v21
	v_add_f32_e32 v15, 1.0, v15
	v_rcp_f32_e32 v21, v21
	v_rcp_f32_e32 v15, v15
	v_pk_fma_f32 v[46:47], v[32:33], v[66:67], v[46:47] op_sel_hi:[0,1,1]
	v_pk_fma_f32 v[46:47], v[34:35], v[52:53], v[46:47] op_sel_hi:[0,1,1]
	v_mul_f32_e32 v21, v23, v21
	v_mul_f32_e32 v15, v19, v15
	ds_write2st64_b32 v155, v21, v15 offset0:44 offset1:46
	v_and_b32_e32 v15, 64, v187
	v_add_u32_e32 v15, 64, v15
	v_cmp_lt_i32_e32 vcc, v16, v15
	s_nop 1
	v_cndmask_b32_e32 v16, v187, v16, vcc
	v_lshlrev_b32_e32 v161, 2, v16
	v_xor_b32_e32 v16, 16, v187
	v_cmp_lt_i32_e32 vcc, v16, v15
	s_nop 1
	v_cndmask_b32_e32 v16, v187, v16, vcc
	v_lshlrev_b32_e32 v160, 2, v16
	v_xor_b32_e32 v16, 8, v187
	v_cmp_lt_i32_e32 vcc, v16, v15
	s_nop 1
	v_cndmask_b32_e32 v16, v187, v16, vcc
	v_lshlrev_b32_e32 v159, 2, v16
	v_xor_b32_e32 v16, 4, v187
	v_cmp_lt_i32_e32 vcc, v16, v15
	s_nop 1
	v_cndmask_b32_e32 v16, v187, v16, vcc
	v_lshlrev_b32_e32 v158, 2, v16
	v_xor_b32_e32 v16, 2, v187
	v_cmp_lt_i32_e32 vcc, v16, v15
	s_nop 1
	v_cndmask_b32_e32 v16, v187, v16, vcc
	v_lshlrev_b32_e32 v29, 2, v16
	v_mul_f32_e32 v16, 0xbfb8aa3b, v46
	v_exp_f32_e32 v16, v16
	s_nop 0
	v_add_f32_e32 v16, 1.0, v16
	v_rcp_f32_e32 v66, v16
	v_mul_f32_e32 v16, 0xbfb8aa3b, v47
	v_exp_f32_e32 v16, v16
	s_nop 0
	v_add_f32_e32 v16, 1.0, v16
	v_rcp_f32_e32 v67, v16
	s_nop 0
	v_pk_mul_f32 v[46:47], v[46:47], v[66:67]
	v_pk_mul_f32 v[66:67], v[56:57], v[58:59]
	v_pk_mul_f32 v[58:59], v[46:47], v[46:47]
	ds_bpermute_b32 v58, v161, v58
	ds_bpermute_b32 v59, v161, v59
	s_waitcnt lgkmcnt(0)
	v_pk_fma_f32 v[58:59], v[46:47], v[46:47], v[58:59]
	ds_bpermute_b32 v68, v160, v58
	ds_bpermute_b32 v69, v160, v59
	s_waitcnt lgkmcnt(0)
	v_pk_add_f32 v[58:59], v[58:59], v[68:69]
	ds_bpermute_b32 v68, v159, v58
	ds_bpermute_b32 v69, v159, v59
	s_waitcnt lgkmcnt(0)
	v_pk_add_f32 v[58:59], v[58:59], v[68:69]
	ds_bpermute_b32 v68, v158, v58
	ds_bpermute_b32 v69, v158, v59
	s_waitcnt lgkmcnt(0)
	v_pk_add_f32 v[58:59], v[58:59], v[68:69]
	ds_bpermute_b32 v68, v29, v58
	ds_bpermute_b32 v69, v29, v59
	s_waitcnt lgkmcnt(0)
	v_pk_add_f32 v[58:59], v[58:59], v[68:69]
	v_mov_b32_e32 v68, v53
	v_pk_fma_f32 v[52:53], v[62:63], v[52:53], v[66:67] op_sel_hi:[1,0,1]
	v_mov_b32_e32 v69, v43
	v_pk_fma_f32 v[52:53], v[32:33], v[60:61], v[52:53] op_sel_hi:[0,1,1]
	v_pk_fma_f32 v[52:53], v[34:35], v[42:43], v[52:53] op_sel_hi:[0,1,1]
	v_mul_f32_e32 v16, 0xbfb8aa3b, v52
	v_exp_f32_e32 v16, v16
	v_pk_mul_f32 v[68:69], v[56:57], v[68:69]
	v_add_f32_e32 v16, 1.0, v16
	v_rcp_f32_e32 v60, v16
	v_mul_f32_e32 v16, 0xbfb8aa3b, v53
	v_exp_f32_e32 v16, v16
	s_nop 0
	v_add_f32_e32 v16, 1.0, v16
	v_rcp_f32_e32 v61, v16
	s_nop 0
	v_pk_mul_f32 v[52:53], v[52:53], v[60:61]
	s_nop 0
	v_pk_mul_f32 v[60:61], v[52:53], v[52:53]
	ds_bpermute_b32 v60, v161, v60
	ds_bpermute_b32 v61, v161, v61
	s_waitcnt lgkmcnt(0)
	v_pk_fma_f32 v[60:61], v[52:53], v[52:53], v[60:61]
	ds_bpermute_b32 v66, v160, v60
	ds_bpermute_b32 v67, v160, v61
	s_waitcnt lgkmcnt(0)
	v_pk_add_f32 v[60:61], v[60:61], v[66:67]
	ds_bpermute_b32 v66, v159, v60
	ds_bpermute_b32 v67, v159, v61
	s_waitcnt lgkmcnt(0)
	v_pk_add_f32 v[60:61], v[60:61], v[66:67]
	ds_bpermute_b32 v66, v158, v60
	ds_bpermute_b32 v67, v158, v61
	s_waitcnt lgkmcnt(0)
	v_pk_add_f32 v[60:61], v[60:61], v[66:67]
	ds_bpermute_b32 v66, v29, v60
	ds_bpermute_b32 v67, v29, v61
	s_waitcnt lgkmcnt(0)
	v_pk_add_f32 v[60:61], v[60:61], v[66:67]
	v_mov_b32_e32 v66, v43
	v_mov_b32_e32 v67, v1
	v_pk_mul_f32 v[66:67], v[56:57], v[66:67]
	v_pk_mov_b32 v[56:57], v[42:43], v[0:1] op_sel:[1,0]
	v_pk_fma_f32 v[42:43], v[62:63], v[42:43], v[68:69] op_sel_hi:[1,0,1]
	s_nop 0
	v_pk_fma_f32 v[42:43], v[32:33], v[56:57], v[42:43] op_sel_hi:[0,1,1]
	v_pk_fma_f32 v[42:43], v[34:35], v[0:1], v[42:43] op_sel_hi:[0,1,1]
	v_mul_f32_e32 v16, 0xbfb8aa3b, v43
	v_exp_f32_e32 v16, v16
	s_nop 0
	v_add_f32_e32 v16, 1.0, v16
	v_rcp_f32_e32 v57, v16
	v_mul_f32_e32 v16, 0xbfb8aa3b, v42
	v_exp_f32_e32 v16, v16
	s_nop 0
	v_add_f32_e32 v16, 1.0, v16
	v_rcp_f32_e32 v56, v16
	s_nop 0
	v_pk_mul_f32 v[42:43], v[42:43], v[56:57]
	s_nop 0
	v_pk_mul_f32 v[56:57], v[42:43], v[42:43]
	ds_bpermute_b32 v57, v161, v57
	ds_bpermute_b32 v56, v161, v56
	s_waitcnt lgkmcnt(0)
	v_pk_fma_f32 v[56:57], v[42:43], v[42:43], v[56:57]
	ds_bpermute_b32 v69, v160, v57
	ds_bpermute_b32 v68, v160, v56
	s_waitcnt lgkmcnt(0)
	v_pk_add_f32 v[56:57], v[56:57], v[68:69]
	ds_bpermute_b32 v69, v159, v57
	ds_bpermute_b32 v68, v159, v56
	s_waitcnt lgkmcnt(0)
	v_pk_add_f32 v[56:57], v[56:57], v[68:69]
	ds_bpermute_b32 v69, v158, v57
	ds_bpermute_b32 v68, v158, v56
	s_waitcnt lgkmcnt(0)
	v_pk_add_f32 v[56:57], v[56:57], v[68:69]
	ds_bpermute_b32 v68, v29, v56
	ds_bpermute_b32 v69, v29, v57
	s_waitcnt lgkmcnt(0)
	v_pk_add_f32 v[56:57], v[56:57], v[68:69]
	v_mov_b32_e32 v68, v49
	v_mov_b32_e32 v69, v48
	v_pk_fma_f32 v[54:55], v[54:55], v[68:69], v[74:75] op_sel_hi:[0,1,1]
	v_pk_fma_f32 v[54:55], v[36:37], v[70:71], v[54:55] op_sel_hi:[0,1,1]
	v_pk_fma_f32 v[54:55], v[38:39], v[44:45], v[54:55] op_sel_hi:[0,1,1]
	v_mul_f32_e32 v16, 0xbfb8aa3b, v54
	v_exp_f32_e32 v16, v16
	s_nop 0
	v_add_f32_e32 v16, 1.0, v16
	v_rcp_f32_e32 v70, v16
	v_mul_f32_e32 v16, 0xbfb8aa3b, v55
	v_exp_f32_e32 v16, v16
	s_nop 0
	v_add_f32_e32 v16, 1.0, v16
	v_rcp_f32_e32 v71, v16
	s_nop 0
	v_pk_mul_f32 v[54:55], v[54:55], v[70:71]
	v_pk_mul_f32 v[70:71], v[48:49], v[50:51]
	v_pk_mul_f32 v[50:51], v[54:55], v[54:55]
	ds_bpermute_b32 v50, v161, v50
	ds_bpermute_b32 v51, v161, v51
	s_waitcnt lgkmcnt(0)
	v_pk_fma_f32 v[50:51], v[54:55], v[54:55], v[50:51]
	ds_bpermute_b32 v74, v160, v50
	ds_bpermute_b32 v75, v160, v51
	s_waitcnt lgkmcnt(0)
	v_pk_add_f32 v[50:51], v[50:51], v[74:75]
	ds_bpermute_b32 v74, v159, v50
	ds_bpermute_b32 v75, v159, v51
	s_waitcnt lgkmcnt(0)
	v_pk_add_f32 v[50:51], v[50:51], v[74:75]
	ds_bpermute_b32 v74, v158, v50
	ds_bpermute_b32 v75, v158, v51
	s_waitcnt lgkmcnt(0)
	v_pk_add_f32 v[50:51], v[50:51], v[74:75]
	ds_bpermute_b32 v74, v29, v50
	ds_bpermute_b32 v75, v29, v51
	s_waitcnt lgkmcnt(0)
	v_pk_add_f32 v[50:51], v[50:51], v[74:75]
	v_mov_b32_e32 v74, v45
	v_pk_fma_f32 v[44:45], v[68:69], v[44:45], v[70:71] op_sel_hi:[1,0,1]
	v_mov_b32_e32 v75, v41
	v_pk_fma_f32 v[44:45], v[36:37], v[64:65], v[44:45] op_sel_hi:[0,1,1]
	v_pk_fma_f32 v[44:45], v[38:39], v[40:41], v[44:45] op_sel_hi:[0,1,1]
	v_mul_f32_e32 v16, 0xbfb8aa3b, v44
	v_exp_f32_e32 v16, v16
	v_pk_mul_f32 v[74:75], v[48:49], v[74:75]
	v_add_f32_e32 v16, 1.0, v16
	v_rcp_f32_e32 v64, v16
	v_mul_f32_e32 v16, 0xbfb8aa3b, v45
	v_exp_f32_e32 v16, v16
	s_nop 0
	v_add_f32_e32 v16, 1.0, v16
	v_rcp_f32_e32 v65, v16
	s_nop 0
	v_pk_mul_f32 v[44:45], v[44:45], v[64:65]
	s_nop 0
	v_pk_mul_f32 v[64:65], v[44:45], v[44:45]
	ds_bpermute_b32 v64, v161, v64
	ds_bpermute_b32 v65, v161, v65
	s_waitcnt lgkmcnt(0)
	v_pk_fma_f32 v[64:65], v[44:45], v[44:45], v[64:65]
	ds_bpermute_b32 v70, v160, v64
	ds_bpermute_b32 v71, v160, v65
	s_waitcnt lgkmcnt(0)
	v_pk_add_f32 v[64:65], v[64:65], v[70:71]
	ds_bpermute_b32 v70, v159, v64
	ds_bpermute_b32 v71, v159, v65
	s_waitcnt lgkmcnt(0)
	v_pk_add_f32 v[64:65], v[64:65], v[70:71]
	ds_bpermute_b32 v70, v158, v64
	ds_bpermute_b32 v71, v158, v65
	s_waitcnt lgkmcnt(0)
	v_pk_add_f32 v[64:65], v[64:65], v[70:71]
	ds_bpermute_b32 v70, v29, v64
	ds_bpermute_b32 v71, v29, v65
	s_waitcnt lgkmcnt(0)
	v_pk_add_f32 v[64:65], v[64:65], v[70:71]
	v_mov_b32_e32 v70, v41
	v_mov_b32_e32 v71, v5
	v_pk_mul_f32 v[70:71], v[48:49], v[70:71]
	v_pk_mov_b32 v[48:49], v[40:41], v[4:5] op_sel:[1,0]
	v_pk_fma_f32 v[40:41], v[68:69], v[40:41], v[74:75] op_sel_hi:[1,0,1]
	s_nop 0
	v_pk_fma_f32 v[40:41], v[36:37], v[48:49], v[40:41] op_sel_hi:[0,1,1]
	v_pk_fma_f32 v[40:41], v[38:39], v[4:5], v[40:41] op_sel_hi:[0,1,1]
	v_mul_f32_e32 v16, 0xbfb8aa3b, v41
	v_exp_f32_e32 v16, v16
	s_nop 0
	v_add_f32_e32 v16, 1.0, v16
	v_rcp_f32_e32 v49, v16
	v_mul_f32_e32 v16, 0xbfb8aa3b, v40
	v_exp_f32_e32 v16, v16
	s_nop 0
	v_add_f32_e32 v16, 1.0, v16
	v_rcp_f32_e32 v48, v16
	s_nop 0
	v_pk_mul_f32 v[40:41], v[40:41], v[48:49]
	s_nop 0
	v_pk_mul_f32 v[48:49], v[40:41], v[40:41]
	ds_bpermute_b32 v49, v161, v49
	ds_bpermute_b32 v48, v161, v48
	s_waitcnt lgkmcnt(0)
	v_pk_fma_f32 v[48:49], v[40:41], v[40:41], v[48:49]
	ds_bpermute_b32 v75, v160, v49
	ds_bpermute_b32 v74, v160, v48
	s_waitcnt lgkmcnt(0)
	v_pk_add_f32 v[48:49], v[48:49], v[74:75]
	ds_bpermute_b32 v75, v159, v49
	ds_bpermute_b32 v74, v159, v48
	s_waitcnt lgkmcnt(0)
	v_pk_add_f32 v[48:49], v[48:49], v[74:75]
	ds_bpermute_b32 v75, v158, v49
	ds_bpermute_b32 v74, v158, v48
	s_waitcnt lgkmcnt(0)
	v_pk_add_f32 v[48:49], v[48:49], v[74:75]
	ds_bpermute_b32 v74, v29, v48
	ds_bpermute_b32 v75, v29, v49
	s_waitcnt lgkmcnt(0)
	v_pk_add_f32 v[48:49], v[48:49], v[74:75]
	v_pk_mov_b32 v[74:75], v[0:1], v[2:3] op_sel:[1,0]
	v_pk_fma_f32 v[0:1], v[62:63], v[0:1], v[66:67] op_sel_hi:[1,0,1]
	s_nop 0
	v_pk_fma_f32 v[0:1], v[32:33], v[74:75], v[0:1] op_sel_hi:[0,1,1]
	v_pk_fma_f32 v[0:1], v[34:35], v[2:3], v[0:1] op_sel_hi:[0,1,1]
	v_mul_f32_e32 v2, 0xbfb8aa3b, v1
	v_exp_f32_e32 v2, v2
	s_nop 0
	v_add_f32_e32 v2, 1.0, v2
	v_rcp_f32_e32 v3, v2
	v_mul_f32_e32 v2, 0xbfb8aa3b, v0
	v_exp_f32_e32 v2, v2
	s_nop 0
	v_add_f32_e32 v2, 1.0, v2
	v_rcp_f32_e32 v2, v2
	s_nop 0
	v_pk_mul_f32 v[32:33], v[0:1], v[2:3]
	s_nop 0
	v_pk_mul_f32 v[0:1], v[32:33], v[32:33]
	ds_bpermute_b32 v1, v161, v1
	ds_bpermute_b32 v0, v161, v0
	s_waitcnt lgkmcnt(0)
	v_pk_fma_f32 v[0:1], v[32:33], v[32:33], v[0:1]
	ds_bpermute_b32 v3, v160, v1
	ds_bpermute_b32 v2, v160, v0
	s_waitcnt lgkmcnt(0)
	v_pk_add_f32 v[0:1], v[0:1], v[2:3]
	ds_bpermute_b32 v3, v159, v1
	ds_bpermute_b32 v2, v159, v0
	s_waitcnt lgkmcnt(0)
	v_pk_add_f32 v[0:1], v[0:1], v[2:3]
	ds_bpermute_b32 v3, v158, v1
	ds_bpermute_b32 v2, v158, v0
	s_waitcnt lgkmcnt(0)
	v_pk_add_f32 v[0:1], v[0:1], v[2:3]
	ds_bpermute_b32 v2, v29, v0
	ds_bpermute_b32 v3, v29, v1
	s_waitcnt lgkmcnt(0)
	v_pk_add_f32 v[0:1], v[0:1], v[2:3]
	v_pk_mov_b32 v[2:3], v[4:5], v[6:7] op_sel:[1,0]
	v_pk_fma_f32 v[4:5], v[68:69], v[4:5], v[70:71] op_sel_hi:[1,0,1]
	s_nop 0
	v_pk_fma_f32 v[2:3], v[36:37], v[2:3], v[4:5] op_sel_hi:[0,1,1]
	v_pk_fma_f32 v[2:3], v[38:39], v[6:7], v[2:3] op_sel_hi:[0,1,1]
	v_mul_f32_e32 v4, 0xbfb8aa3b, v3
	v_exp_f32_e32 v4, v4
	s_nop 0
	v_add_f32_e32 v4, 1.0, v4
	v_rcp_f32_e32 v5, v4
	v_mul_f32_e32 v4, 0xbfb8aa3b, v2
	v_exp_f32_e32 v4, v4
	s_nop 0
	v_add_f32_e32 v4, 1.0, v4
	v_rcp_f32_e32 v4, v4
	s_nop 0
	v_pk_mul_f32 v[34:35], v[2:3], v[4:5]
	s_nop 0
	v_pk_mul_f32 v[2:3], v[34:35], v[34:35]
	ds_bpermute_b32 v3, v161, v3
	ds_bpermute_b32 v2, v161, v2
	s_waitcnt lgkmcnt(0)
	v_pk_fma_f32 v[2:3], v[34:35], v[34:35], v[2:3]
	ds_bpermute_b32 v5, v160, v3
	ds_bpermute_b32 v4, v160, v2
	s_waitcnt lgkmcnt(0)
	v_pk_add_f32 v[2:3], v[2:3], v[4:5]
	ds_bpermute_b32 v5, v159, v3
	ds_bpermute_b32 v4, v159, v2
	s_waitcnt lgkmcnt(0)
	v_pk_add_f32 v[2:3], v[2:3], v[4:5]
	ds_bpermute_b32 v5, v158, v3
	ds_bpermute_b32 v4, v158, v2
	s_waitcnt lgkmcnt(0)
	v_pk_add_f32 v[2:3], v[2:3], v[4:5]
	ds_bpermute_b32 v4, v29, v2
	ds_bpermute_b32 v5, v29, v3
	s_waitcnt lgkmcnt(0)
	v_pk_add_f32 v[2:3], v[2:3], v[4:5]
	v_xor_b32_e32 v4, 1, v187
	v_cmp_lt_i32_e32 vcc, v4, v15
	s_nop 1
	v_cndmask_b32_e32 v4, v187, v4, vcc
	v_lshlrev_b32_e32 v163, 2, v4
	ds_bpermute_b32 v66, v163, v58
	ds_bpermute_b32 v68, v163, v50
	ds_bpermute_b32 v67, v163, v59
	ds_bpermute_b32 v69, v163, v51
	ds_bpermute_b32 v70, v163, v60
	ds_bpermute_b32 v62, v163, v64
	ds_bpermute_b32 v71, v163, v61
	ds_bpermute_b32 v63, v163, v65
	ds_bpermute_b32 v6, v163, v56
	ds_bpermute_b32 v36, v163, v48
	ds_bpermute_b32 v7, v163, v57
	ds_bpermute_b32 v37, v163, v49
	ds_bpermute_b32 v38, v163, v0
	ds_bpermute_b32 v4, v163, v2
	ds_bpermute_b32 v39, v163, v1
	ds_bpermute_b32 v5, v163, v3
	s_and_saveexec_b64 s[6:7], s[4:5]
	s_cbranch_execz .LBB0_610
	s_waitcnt lgkmcnt(13)
	v_pk_add_f32 v[58:59], v[58:59], v[66:67]
	s_waitcnt lgkmcnt(9)
	v_pk_add_f32 v[60:61], v[60:61], v[70:71]
	v_pk_add_f32 v[66:67], v[50:51], v[68:69]
	ds_write_b128 v162, v[58:61] offset:20480
	s_waitcnt lgkmcnt(9)
	v_pk_add_f32 v[68:69], v[64:65], v[62:63]
	s_waitcnt lgkmcnt(6)
	v_pk_add_f32 v[56:57], v[56:57], v[6:7]
	s_waitcnt lgkmcnt(5)
	v_pk_add_f32 v[36:37], v[48:49], v[36:37]
	s_waitcnt lgkmcnt(2)
	v_pk_add_f32 v[58:59], v[0:1], v[38:39]
	s_waitcnt lgkmcnt(1)
	v_pk_add_f32 v[38:39], v[2:3], v[4:5]
	ds_write_b128 v162, v[66:69] offset:20512
	ds_write_b128 v162, v[56:59] offset:20496
	ds_write_b128 v162, v[36:39] offset:20528
